# NSA top-k selection done in registers (29 candidates, 5 argmax rounds) instead of serial LDS loop
# speedup vs baseline: 1.0038x; 1.0038x over previous
; DEVI void nsa_item(const Params& p, int l, int item, char* lds_raw, volatile int* nsa_cnt) {
;     ...
;   __syncthreads();
;   if (tid < 64) {
;     const int cur = qt;
;     unsigned forced = 1u | (1u << cur) | (cur > 0 ? (1u << (cur - 1)) : 0u);
;     unsigned sel = forced;
;     int cnt = __popc(forced);
;     for (int J = 0; J < 32; ++J) {
;       float v = Gs[tid * 33 + J];
;       if (J > 0) v += Ls_[tid * 33 + J - 1];
;       Pb[tid * 33 + J] = v;
;     }
.LBB0_489:
	s_barrier
	v_cmp_gt_i32_e32 vcc, 64, v83
	s_mov_b64 s[4:5], exec
	v_readlane_b32 s88, v242, 47
	v_readlane_b32 s94, v242, 53
	v_readlane_b32 s95, v242, 54
	s_and_b64 s[0:1], s[4:5], vcc
	v_readlane_b32 s89, v242, 48
	v_readlane_b32 s90, v242, 49
	v_readlane_b32 s91, v242, 50
	v_readlane_b32 s92, v242, 51
	v_readlane_b32 s93, v242, 52
	s_mov_b32 s86, s30
	s_mov_b32 s87, s24
	s_mov_b64 s[96:97], s[6:7]
	s_mov_b64 s[6:7], s[18:19]
	s_mov_b32 s18, s29
	s_mov_b32 s19, s33
	s_mov_b32 s33, s22
	s_mov_b32 s22, s13
	v_readlane_b32 s24, v242, 42
	v_readlane_b32 s13, v242, 41
	s_movk_i32 s94, 0x100
	s_movk_i32 s95, 0x880
	s_movk_i32 s83, 0x440
	s_movk_i32 s72, 0x1800
	s_mov_b64 s[2:3], s[16:17]
	s_mov_b32 s16, 0x5040100
	s_mov_b32 s17, 0xa728000
	s_mov_b64 exec, s[0:1]
	s_cbranch_execz .LBB0_498
	s_sub_i32 s1, 30, s28
	s_lshr_b32 s0, 0x80000000, s28
	s_lshl_b32 s1, 1, s1
	s_cmp_lt_i32 s28, 31
	s_cselect_b32 s1, s1, 0
	s_or_b32 s0, s0, s1
	s_movk_i32 s1, 0x84
	v_mul_lo_u32 v53, v83, s1
	v_add_u32_e32 v52, s26, v53
	v_add_u32_e32 v50, 0x9000, v52
	v_add_u32_e32 v54, 0x9004, v52
	v_add_u32_e32 v56, 0xb100, v52
	ds_read2_b32 v[50:51], v50 offset1:31
	ds_read2_b32 v[54:55], v54 offset1:1
	ds_read2_b32 v[56:57], v56 offset1:1
	v_add_u32_e32 v58, 0xd204, v52
	s_or_b32 s0, s0, 1
	s_bcnt1_i32_b32 s30, s0
	s_sub_i32 s38, 32, s28
	s_waitcnt lgkmcnt(0)
	v_pk_add_f32 v[54:55], v[54:55], v[56:57]
	ds_write2_b32 v58, v54, v55 offset1:1
	v_add_u32_e32 v54, 0x900c, v52
	v_add_u32_e32 v56, 0xb108, v52
	ds_read2_b32 v[54:55], v54 offset1:1
	ds_read2_b32 v[56:57], v56 offset1:1
	v_add_u32_e32 v58, 0xd20c, v52
	s_mov_b64 s[36:37], 0
	s_waitcnt lgkmcnt(0)
	v_pk_add_f32 v[54:55], v[54:55], v[56:57]
	ds_write2_b32 v58, v54, v55 offset1:1
	v_add_u32_e32 v54, 0x9014, v52
	v_add_u32_e32 v56, 0xb110, v52
	ds_read2_b32 v[54:55], v54 offset1:1
	ds_read2_b32 v[56:57], v56 offset1:1
	v_add_u32_e32 v58, 0xd214, v52
	s_waitcnt lgkmcnt(0)
	v_pk_add_f32 v[54:55], v[54:55], v[56:57]
	ds_write2_b32 v58, v54, v55 offset1:1
	v_add_u32_e32 v54, 0x901c, v52
	v_add_u32_e32 v56, 0xb118, v52
	ds_read2_b32 v[54:55], v54 offset1:1
	ds_read2_b32 v[56:57], v56 offset1:1
	v_add_u32_e32 v58, 0xd21c, v52
	s_waitcnt lgkmcnt(0)
	v_pk_add_f32 v[54:55], v[54:55], v[56:57]
	ds_write2_b32 v58, v54, v55 offset1:1
	v_add_u32_e32 v54, 0x9024, v52
	v_add_u32_e32 v56, 0xb120, v52
	ds_read2_b32 v[54:55], v54 offset1:1
	ds_read2_b32 v[56:57], v56 offset1:1
	v_add_u32_e32 v58, 0xd224, v52
	s_waitcnt lgkmcnt(0)
	v_pk_add_f32 v[54:55], v[54:55], v[56:57]
	ds_write2_b32 v58, v54, v55 offset1:1
	v_add_u32_e32 v54, 0x902c, v52
	v_add_u32_e32 v56, 0xb128, v52
	ds_read2_b32 v[54:55], v54 offset1:1
	ds_read2_b32 v[56:57], v56 offset1:1
	v_add_u32_e32 v58, 0xd22c, v52
	s_waitcnt lgkmcnt(0)
	v_pk_add_f32 v[54:55], v[54:55], v[56:57]
	ds_write2_b32 v58, v54, v55 offset1:1
	v_add_u32_e32 v54, 0x9034, v52
	v_add_u32_e32 v56, 0xb130, v52
	ds_read2_b32 v[54:55], v54 offset1:1
	ds_read2_b32 v[56:57], v56 offset1:1
	v_add_u32_e32 v58, 0xd234, v52
	s_waitcnt lgkmcnt(0)
	v_pk_add_f32 v[54:55], v[54:55], v[56:57]
	ds_write2_b32 v58, v54, v55 offset1:1
	v_add_u32_e32 v54, 0x903c, v52
	v_add_u32_e32 v56, 0xb138, v52
	ds_read2_b32 v[54:55], v54 offset1:1
	ds_read2_b32 v[56:57], v56 offset1:1
	v_add_u32_e32 v58, 0xd23c, v52
	s_waitcnt lgkmcnt(0)
	v_pk_add_f32 v[54:55], v[54:55], v[56:57]
	ds_write2_b32 v58, v54, v55 offset1:1
	v_add_u32_e32 v54, 0x9044, v52
	v_add_u32_e32 v56, 0xb140, v52
	ds_read2_b32 v[54:55], v54 offset1:1
	ds_read2_b32 v[56:57], v56 offset1:1
	v_add_u32_e32 v58, 0xd244, v52
	s_waitcnt lgkmcnt(0)
	v_pk_add_f32 v[54:55], v[54:55], v[56:57]
	ds_write2_b32 v58, v54, v55 offset1:1
	v_add_u32_e32 v54, 0x904c, v52
	v_add_u32_e32 v56, 0xb148, v52
	ds_read2_b32 v[54:55], v54 offset1:1
	ds_read2_b32 v[56:57], v56 offset1:1
	v_add_u32_e32 v58, 0xd24c, v52
	s_waitcnt lgkmcnt(0)
	v_pk_add_f32 v[54:55], v[54:55], v[56:57]
	ds_write2_b32 v58, v54, v55 offset1:1
	v_add_u32_e32 v54, 0x9054, v52
	v_add_u32_e32 v56, 0xb150, v52
	ds_read2_b32 v[54:55], v54 offset1:1
	ds_read2_b32 v[56:57], v56 offset1:1
	v_add_u32_e32 v58, 0xd254, v52
	s_waitcnt lgkmcnt(0)
	v_pk_add_f32 v[54:55], v[54:55], v[56:57]
	ds_write2_b32 v58, v54, v55 offset1:1
	v_add_u32_e32 v54, 0x905c, v52
	v_add_u32_e32 v56, 0xb158, v52
	ds_read2_b32 v[54:55], v54 offset1:1
	ds_read2_b32 v[56:57], v56 offset1:1
	v_add_u32_e32 v58, 0xd25c, v52
	s_waitcnt lgkmcnt(0)
	v_pk_add_f32 v[54:55], v[54:55], v[56:57]
	ds_write2_b32 v58, v54, v55 offset1:1
	v_add_u32_e32 v54, 0x9064, v52
	v_add_u32_e32 v56, 0xb160, v52
	ds_read2_b32 v[54:55], v54 offset1:1
	ds_read2_b32 v[56:57], v56 offset1:1
	v_add_u32_e32 v58, 0xd264, v52
	s_waitcnt lgkmcnt(0)
	v_pk_add_f32 v[54:55], v[54:55], v[56:57]
	ds_write2_b32 v58, v54, v55 offset1:1
	v_add_u32_e32 v54, 0x906c, v52
	v_add_u32_e32 v56, 0xb168, v52
	ds_read2_b32 v[54:55], v54 offset1:1
	ds_read2_b32 v[56:57], v56 offset1:1
	v_add_u32_e32 v58, 0xd26c, v52
	s_waitcnt lgkmcnt(0)
	v_pk_add_f32 v[54:55], v[54:55], v[56:57]
	ds_write2_b32 v58, v54, v55 offset1:1
	v_add_u32_e32 v54, 0x9074, v52
	v_add_u32_e32 v56, 0xb170, v52
	ds_read2_b32 v[54:55], v54 offset1:1
	ds_read2_b32 v[56:57], v56 offset1:1
	v_add_u32_e32 v58, 0xd274, v52
	s_waitcnt lgkmcnt(0)
	v_pk_add_f32 v[54:55], v[54:55], v[56:57]
	ds_write2_b32 v58, v54, v55 offset1:1
	ds_read_b32 v54, v52 offset:45432
	s_waitcnt lgkmcnt(0)
; DEVI void nsa_item(const Params& p, int l, int item, char* lds_raw, volatile int* nsa_cnt) {
;     ...
;     while (cnt < 8) {
;       int best = -1;
;       float bv = -1.f;
;       for (int J = 0; J <= cur; ++J) {
;         float v = Pb[tid * 33 + J];
;         if (!((sel >> J) & 1u) && v > bv) { bv = v; best = J; }
;       }
;       if (best < 0) break;
;       sel |= 1u << best;
;       ++cnt;
;     }
	v_add_f32_e32 v51, v51, v54
	v_add_u32_e32 v54, 0xd000, v52
	ds_write2_b32 v54, v50, v51 offset0:128 offset1:159
	v_add_u32_e32 v50, s21, v53
	v_mov_b32_e32 v51, s0
	ds_read2_b32 v[54:55], v50 offset0:1 offset1:2
	ds_read2_b32 v[56:57], v50 offset0:3 offset1:4
	ds_read2_b32 v[58:59], v50 offset0:5 offset1:6
	ds_read2_b32 v[60:61], v50 offset0:7 offset1:8
	ds_read2_b32 v[62:63], v50 offset0:9 offset1:10
	ds_read2_b32 v[64:65], v50 offset0:11 offset1:12
	ds_read2_b32 v[66:67], v50 offset0:13 offset1:14
	ds_read2_b32 v[68:69], v50 offset0:15 offset1:16
	ds_read2_b32 v[70:71], v50 offset0:17 offset1:18
	ds_read2_b32 v[72:73], v50 offset0:19 offset1:20
	ds_read2_b32 v[74:75], v50 offset0:21 offset1:22
	ds_read2_b32 v[76:77], v50 offset0:23 offset1:24
	ds_read2_b32 v[78:79], v50 offset0:25 offset1:26
	ds_read2_b32 v[80:81], v50 offset0:27 offset1:28
	ds_read2_b32 v[234:235], v50 offset0:29 offset1:30
	v_mov_b32_e32 v240, s38
	v_mov_b32_e32 v238, -2.0
	s_waitcnt lgkmcnt(0)
	v_cmp_ge_u32_e64 vcc, 3, v240
	v_cmp_ge_u32_e64 s[0:1], 4, v240
	v_cmp_ge_u32_e64 s[40:41], 5, v240
	v_cndmask_b32_e64 v54, v54, v238, vcc
	v_cmp_ge_u32_e64 vcc, 6, v240
	v_cndmask_b32_e64 v55, v55, v238, s[0:1]
	v_cmp_ge_u32_e64 s[0:1], 7, v240
	v_cndmask_b32_e64 v56, v56, v238, s[40:41]
	v_cmp_ge_u32_e64 s[40:41], 8, v240
	v_cndmask_b32_e64 v57, v57, v238, vcc
	v_cmp_ge_u32_e64 vcc, 9, v240
	v_cndmask_b32_e64 v58, v58, v238, s[0:1]
	v_cmp_ge_u32_e64 s[0:1], 10, v240
	v_cndmask_b32_e64 v59, v59, v238, s[40:41]
	v_cmp_ge_u32_e64 s[40:41], 11, v240
	v_cndmask_b32_e64 v60, v60, v238, vcc
	v_cmp_ge_u32_e64 vcc, 12, v240
	v_cndmask_b32_e64 v61, v61, v238, s[0:1]
	v_cmp_ge_u32_e64 s[0:1], 13, v240
	v_cndmask_b32_e64 v62, v62, v238, s[40:41]
	v_cmp_ge_u32_e64 s[40:41], 14, v240
	v_cndmask_b32_e64 v63, v63, v238, vcc
	v_cmp_ge_u32_e64 vcc, 15, v240
	v_cndmask_b32_e64 v64, v64, v238, s[0:1]
	v_cmp_ge_u32_e64 s[0:1], 16, v240
	v_cndmask_b32_e64 v65, v65, v238, s[40:41]
	v_cmp_ge_u32_e64 s[40:41], 17, v240
	v_cndmask_b32_e64 v66, v66, v238, vcc
	v_cmp_ge_u32_e64 vcc, 18, v240
	v_cndmask_b32_e64 v67, v67, v238, s[0:1]
	v_cmp_ge_u32_e64 s[0:1], 19, v240
	v_cndmask_b32_e64 v68, v68, v238, s[40:41]
	v_cmp_ge_u32_e64 s[40:41], 20, v240
	v_cndmask_b32_e64 v69, v69, v238, vcc
	v_cmp_ge_u32_e64 vcc, 21, v240
	v_cndmask_b32_e64 v70, v70, v238, s[0:1]
	v_cmp_ge_u32_e64 s[0:1], 22, v240
	v_cndmask_b32_e64 v71, v71, v238, s[40:41]
	v_cmp_ge_u32_e64 s[40:41], 23, v240
	v_cndmask_b32_e64 v72, v72, v238, vcc
	v_cmp_ge_u32_e64 vcc, 24, v240
	v_cndmask_b32_e64 v73, v73, v238, s[0:1]
	v_cmp_ge_u32_e64 s[0:1], 25, v240
	v_cndmask_b32_e64 v74, v74, v238, s[40:41]
	v_cmp_ge_u32_e64 s[40:41], 26, v240
	v_cndmask_b32_e64 v75, v75, v238, vcc
	v_cmp_ge_u32_e64 vcc, 27, v240
	v_cndmask_b32_e64 v76, v76, v238, s[0:1]
	v_cmp_ge_u32_e64 s[0:1], 28, v240
	v_cndmask_b32_e64 v77, v77, v238, s[40:41]
	v_cmp_ge_u32_e64 s[40:41], 29, v240
	v_cndmask_b32_e64 v78, v78, v238, vcc
	v_cmp_ge_u32_e64 vcc, 30, v240
	v_cndmask_b32_e64 v79, v79, v238, s[0:1]
	v_cmp_ge_u32_e64 s[0:1], 31, v240
	v_cndmask_b32_e64 v80, v80, v238, s[40:41]
	s_nop 0
	v_cndmask_b32_e64 v81, v81, v238, vcc
	s_nop 0
	v_cndmask_b32_e64 v234, v234, v238, s[0:1]
	v_mov_b32_e32 v236, -1.0
	v_mov_b32_e32 v237, -1
	v_cmp_gt_f32_e32 vcc, v54, v236
	s_nop 1
	v_cndmask_b32_e32 v236, v236, v54, vcc
	v_cndmask_b32_e64 v237, v237, 1, vcc
	v_cmp_gt_f32_e32 vcc, v55, v236
	s_nop 1
	v_cndmask_b32_e32 v236, v236, v55, vcc
	v_cndmask_b32_e64 v237, v237, 2, vcc
	v_cmp_gt_f32_e32 vcc, v56, v236
	s_nop 1
	v_cndmask_b32_e32 v236, v236, v56, vcc
	v_cndmask_b32_e64 v237, v237, 3, vcc
	v_cmp_gt_f32_e32 vcc, v57, v236
	s_nop 1
	v_cndmask_b32_e32 v236, v236, v57, vcc
	v_cndmask_b32_e64 v237, v237, 4, vcc
	v_cmp_gt_f32_e32 vcc, v58, v236
	s_nop 1
	v_cndmask_b32_e32 v236, v236, v58, vcc
	v_cndmask_b32_e64 v237, v237, 5, vcc
	v_cmp_gt_f32_e32 vcc, v59, v236
	s_nop 1
	v_cndmask_b32_e32 v236, v236, v59, vcc
	v_cndmask_b32_e64 v237, v237, 6, vcc
	v_cmp_gt_f32_e32 vcc, v60, v236
	s_nop 1
	v_cndmask_b32_e32 v236, v236, v60, vcc
	v_cndmask_b32_e64 v237, v237, 7, vcc
	v_cmp_gt_f32_e32 vcc, v61, v236
	s_nop 1
	v_cndmask_b32_e32 v236, v236, v61, vcc
	v_cndmask_b32_e64 v237, v237, 8, vcc
	v_cmp_gt_f32_e32 vcc, v62, v236
	s_nop 1
	v_cndmask_b32_e32 v236, v236, v62, vcc
	v_cndmask_b32_e64 v237, v237, 9, vcc
	v_cmp_gt_f32_e32 vcc, v63, v236
	s_nop 1
	v_cndmask_b32_e32 v236, v236, v63, vcc
	v_cndmask_b32_e64 v237, v237, 10, vcc
	v_cmp_gt_f32_e32 vcc, v64, v236
	s_nop 1
	v_cndmask_b32_e32 v236, v236, v64, vcc
	v_cndmask_b32_e64 v237, v237, 11, vcc
	v_cmp_gt_f32_e32 vcc, v65, v236
	s_nop 1
	v_cndmask_b32_e32 v236, v236, v65, vcc
	v_cndmask_b32_e64 v237, v237, 12, vcc
	v_cmp_gt_f32_e32 vcc, v66, v236
	s_nop 1
	v_cndmask_b32_e32 v236, v236, v66, vcc
	v_cndmask_b32_e64 v237, v237, 13, vcc
	v_cmp_gt_f32_e32 vcc, v67, v236
	s_nop 1
	v_cndmask_b32_e32 v236, v236, v67, vcc
	v_cndmask_b32_e64 v237, v237, 14, vcc
	v_cmp_gt_f32_e32 vcc, v68, v236
	s_nop 1
	v_cndmask_b32_e32 v236, v236, v68, vcc
	v_cndmask_b32_e64 v237, v237, 15, vcc
	v_cmp_gt_f32_e32 vcc, v69, v236
	s_nop 1
	v_cndmask_b32_e32 v236, v236, v69, vcc
	v_cndmask_b32_e64 v237, v237, 16, vcc
	v_cmp_gt_f32_e32 vcc, v70, v236
	s_nop 1
	v_cndmask_b32_e32 v236, v236, v70, vcc
	v_cndmask_b32_e64 v237, v237, 17, vcc
	v_cmp_gt_f32_e32 vcc, v71, v236
	s_nop 1
	v_cndmask_b32_e32 v236, v236, v71, vcc
	v_cndmask_b32_e64 v237, v237, 18, vcc
	v_cmp_gt_f32_e32 vcc, v72, v236
	s_nop 1
	v_cndmask_b32_e32 v236, v236, v72, vcc
	v_cndmask_b32_e64 v237, v237, 19, vcc
	v_cmp_gt_f32_e32 vcc, v73, v236
	s_nop 1
	v_cndmask_b32_e32 v236, v236, v73, vcc
; DEVI void nsa_item(const Params& p, int l, int item, char* lds_raw, volatile int* nsa_cnt) {
;     ...
;     while (cnt < 8) {
;       int best = -1;
;       float bv = -1.f;
;       for (int J = 0; J <= cur; ++J) {
;         float v = Pb[tid * 33 + J];
;         if (!((sel >> J) & 1u) && v > bv) { bv = v; best = J; }
;       }
;       if (best < 0) break;
;       sel |= 1u << best;
;       ++cnt;
;     }
	v_cndmask_b32_e64 v237, v237, 20, vcc
	v_cmp_gt_f32_e32 vcc, v74, v236
	s_nop 1
	v_cndmask_b32_e32 v236, v236, v74, vcc
	v_cndmask_b32_e64 v237, v237, 21, vcc
	v_cmp_gt_f32_e32 vcc, v75, v236
	s_nop 1
	v_cndmask_b32_e32 v236, v236, v75, vcc
	v_cndmask_b32_e64 v237, v237, 22, vcc
	v_cmp_gt_f32_e32 vcc, v76, v236
	s_nop 1
	v_cndmask_b32_e32 v236, v236, v76, vcc
	v_cndmask_b32_e64 v237, v237, 23, vcc
	v_cmp_gt_f32_e32 vcc, v77, v236
	s_nop 1
	v_cndmask_b32_e32 v236, v236, v77, vcc
	v_cndmask_b32_e64 v237, v237, 24, vcc
	v_cmp_gt_f32_e32 vcc, v78, v236
	s_nop 1
	v_cndmask_b32_e32 v236, v236, v78, vcc
	v_cndmask_b32_e64 v237, v237, 25, vcc
	v_cmp_gt_f32_e32 vcc, v79, v236
	s_nop 1
	v_cndmask_b32_e32 v236, v236, v79, vcc
	v_cndmask_b32_e64 v237, v237, 26, vcc
	v_cmp_gt_f32_e32 vcc, v80, v236
	s_nop 1
	v_cndmask_b32_e32 v236, v236, v80, vcc
	v_cndmask_b32_e64 v237, v237, 27, vcc
	v_cmp_gt_f32_e32 vcc, v81, v236
	s_nop 1
	v_cndmask_b32_e32 v236, v236, v81, vcc
	v_cndmask_b32_e64 v237, v237, 28, vcc
	v_cmp_gt_f32_e32 vcc, v234, v236
	s_nop 1
	v_cndmask_b32_e32 v236, v236, v234, vcc
	v_cndmask_b32_e64 v237, v237, 29, vcc
	v_cmp_le_i32_e32 vcc, 0, v237
	v_lshlrev_b32_e32 v239, v237, v224
	s_nop 0
	v_cndmask_b32_e32 v239, 0, v239, vcc
	v_or_b32_e32 v51, v51, v239
	v_cmp_eq_u32_e64 vcc, 1, v237
	v_cmp_eq_u32_e64 s[0:1], 2, v237
	v_cmp_eq_u32_e64 s[40:41], 3, v237
	v_cndmask_b32_e64 v54, v54, v238, vcc
	v_cmp_eq_u32_e64 vcc, 4, v237
	v_cndmask_b32_e64 v55, v55, v238, s[0:1]
	v_cmp_eq_u32_e64 s[0:1], 5, v237
	v_cndmask_b32_e64 v56, v56, v238, s[40:41]
	v_cmp_eq_u32_e64 s[40:41], 6, v237
	v_cndmask_b32_e64 v57, v57, v238, vcc
	v_cmp_eq_u32_e64 vcc, 7, v237
	v_cndmask_b32_e64 v58, v58, v238, s[0:1]
	v_cmp_eq_u32_e64 s[0:1], 8, v237
	v_cndmask_b32_e64 v59, v59, v238, s[40:41]
	v_cmp_eq_u32_e64 s[40:41], 9, v237
	v_cndmask_b32_e64 v60, v60, v238, vcc
	v_cmp_eq_u32_e64 vcc, 10, v237
	v_cndmask_b32_e64 v61, v61, v238, s[0:1]
	v_cmp_eq_u32_e64 s[0:1], 11, v237
	v_cndmask_b32_e64 v62, v62, v238, s[40:41]
	v_cmp_eq_u32_e64 s[40:41], 12, v237
	v_cndmask_b32_e64 v63, v63, v238, vcc
	v_cmp_eq_u32_e64 vcc, 13, v237
	v_cndmask_b32_e64 v64, v64, v238, s[0:1]
	v_cmp_eq_u32_e64 s[0:1], 14, v237
	v_cndmask_b32_e64 v65, v65, v238, s[40:41]
	v_cmp_eq_u32_e64 s[40:41], 15, v237
	v_cndmask_b32_e64 v66, v66, v238, vcc
	v_cmp_eq_u32_e64 vcc, 16, v237
	v_cndmask_b32_e64 v67, v67, v238, s[0:1]
	v_cmp_eq_u32_e64 s[0:1], 17, v237
	v_cndmask_b32_e64 v68, v68, v238, s[40:41]
	v_cmp_eq_u32_e64 s[40:41], 18, v237
	v_cndmask_b32_e64 v69, v69, v238, vcc
	v_cmp_eq_u32_e64 vcc, 19, v237
	v_cndmask_b32_e64 v70, v70, v238, s[0:1]
	v_cmp_eq_u32_e64 s[0:1], 20, v237
	v_cndmask_b32_e64 v71, v71, v238, s[40:41]
	v_cmp_eq_u32_e64 s[40:41], 21, v237
	v_cndmask_b32_e64 v72, v72, v238, vcc
	v_cmp_eq_u32_e64 vcc, 22, v237
	v_cndmask_b32_e64 v73, v73, v238, s[0:1]
	v_cmp_eq_u32_e64 s[0:1], 23, v237
	v_cndmask_b32_e64 v74, v74, v238, s[40:41]
	v_cmp_eq_u32_e64 s[40:41], 24, v237
	v_cndmask_b32_e64 v75, v75, v238, vcc
	v_cmp_eq_u32_e64 vcc, 25, v237
	v_cndmask_b32_e64 v76, v76, v238, s[0:1]
	v_cmp_eq_u32_e64 s[0:1], 26, v237
	v_cndmask_b32_e64 v77, v77, v238, s[40:41]
	v_cmp_eq_u32_e64 s[40:41], 27, v237
	v_cndmask_b32_e64 v78, v78, v238, vcc
	v_cmp_eq_u32_e64 vcc, 28, v237
	v_cndmask_b32_e64 v79, v79, v238, s[0:1]
	v_cmp_eq_u32_e64 s[0:1], 29, v237
	v_cndmask_b32_e64 v80, v80, v238, s[40:41]
	s_nop 0
	v_cndmask_b32_e64 v81, v81, v238, vcc
	s_nop 0
	v_cndmask_b32_e64 v234, v234, v238, s[0:1]
	v_mov_b32_e32 v236, -1.0
	v_mov_b32_e32 v237, -1
	v_cmp_gt_f32_e32 vcc, v54, v236
	s_nop 1
	v_cndmask_b32_e32 v236, v236, v54, vcc
	v_cndmask_b32_e64 v237, v237, 1, vcc
	v_cmp_gt_f32_e32 vcc, v55, v236
	s_nop 1
	v_cndmask_b32_e32 v236, v236, v55, vcc
	v_cndmask_b32_e64 v237, v237, 2, vcc
	v_cmp_gt_f32_e32 vcc, v56, v236
	s_nop 1
	v_cndmask_b32_e32 v236, v236, v56, vcc
	v_cndmask_b32_e64 v237, v237, 3, vcc
	v_cmp_gt_f32_e32 vcc, v57, v236
	s_nop 1
	v_cndmask_b32_e32 v236, v236, v57, vcc
	v_cndmask_b32_e64 v237, v237, 4, vcc
	v_cmp_gt_f32_e32 vcc, v58, v236
	s_nop 1
	v_cndmask_b32_e32 v236, v236, v58, vcc
	v_cndmask_b32_e64 v237, v237, 5, vcc
	v_cmp_gt_f32_e32 vcc, v59, v236
	s_nop 1
	v_cndmask_b32_e32 v236, v236, v59, vcc
	v_cndmask_b32_e64 v237, v237, 6, vcc
	v_cmp_gt_f32_e32 vcc, v60, v236
	s_nop 1
	v_cndmask_b32_e32 v236, v236, v60, vcc
	v_cndmask_b32_e64 v237, v237, 7, vcc
	v_cmp_gt_f32_e32 vcc, v61, v236
	s_nop 1
	v_cndmask_b32_e32 v236, v236, v61, vcc
	v_cndmask_b32_e64 v237, v237, 8, vcc
	v_cmp_gt_f32_e32 vcc, v62, v236
	s_nop 1
	v_cndmask_b32_e32 v236, v236, v62, vcc
	v_cndmask_b32_e64 v237, v237, 9, vcc
	v_cmp_gt_f32_e32 vcc, v63, v236
	s_nop 1
	v_cndmask_b32_e32 v236, v236, v63, vcc
	v_cndmask_b32_e64 v237, v237, 10, vcc
	v_cmp_gt_f32_e32 vcc, v64, v236
	s_nop 1
	v_cndmask_b32_e32 v236, v236, v64, vcc
	v_cndmask_b32_e64 v237, v237, 11, vcc
	v_cmp_gt_f32_e32 vcc, v65, v236
	s_nop 1
	v_cndmask_b32_e32 v236, v236, v65, vcc
	v_cndmask_b32_e64 v237, v237, 12, vcc
	v_cmp_gt_f32_e32 vcc, v66, v236
	s_nop 1
	v_cndmask_b32_e32 v236, v236, v66, vcc
	v_cndmask_b32_e64 v237, v237, 13, vcc
	v_cmp_gt_f32_e32 vcc, v67, v236
	s_nop 1
	v_cndmask_b32_e32 v236, v236, v67, vcc
	v_cndmask_b32_e64 v237, v237, 14, vcc
	v_cmp_gt_f32_e32 vcc, v68, v236
	s_nop 1
	v_cndmask_b32_e32 v236, v236, v68, vcc
	v_cndmask_b32_e64 v237, v237, 15, vcc
	v_cmp_gt_f32_e32 vcc, v69, v236
	s_nop 1
	v_cndmask_b32_e32 v236, v236, v69, vcc
	v_cndmask_b32_e64 v237, v237, 16, vcc
	v_cmp_gt_f32_e32 vcc, v70, v236
	s_nop 1
	v_cndmask_b32_e32 v236, v236, v70, vcc
	v_cndmask_b32_e64 v237, v237, 17, vcc
	v_cmp_gt_f32_e32 vcc, v71, v236
	s_nop 1
; DEVI void nsa_item(const Params& p, int l, int item, char* lds_raw, volatile int* nsa_cnt) {
;     ...
;     while (cnt < 8) {
;       int best = -1;
;       float bv = -1.f;
;       for (int J = 0; J <= cur; ++J) {
;         float v = Pb[tid * 33 + J];
;         if (!((sel >> J) & 1u) && v > bv) { bv = v; best = J; }
;       }
;       if (best < 0) break;
;       sel |= 1u << best;
;       ++cnt;
;     }
	v_cndmask_b32_e32 v236, v236, v71, vcc
	v_cndmask_b32_e64 v237, v237, 18, vcc
	v_cmp_gt_f32_e32 vcc, v72, v236
	s_nop 1
	v_cndmask_b32_e32 v236, v236, v72, vcc
	v_cndmask_b32_e64 v237, v237, 19, vcc
	v_cmp_gt_f32_e32 vcc, v73, v236
	s_nop 1
	v_cndmask_b32_e32 v236, v236, v73, vcc
	v_cndmask_b32_e64 v237, v237, 20, vcc
	v_cmp_gt_f32_e32 vcc, v74, v236
	s_nop 1
	v_cndmask_b32_e32 v236, v236, v74, vcc
	v_cndmask_b32_e64 v237, v237, 21, vcc
	v_cmp_gt_f32_e32 vcc, v75, v236
	s_nop 1
	v_cndmask_b32_e32 v236, v236, v75, vcc
	v_cndmask_b32_e64 v237, v237, 22, vcc
	v_cmp_gt_f32_e32 vcc, v76, v236
	s_nop 1
	v_cndmask_b32_e32 v236, v236, v76, vcc
	v_cndmask_b32_e64 v237, v237, 23, vcc
	v_cmp_gt_f32_e32 vcc, v77, v236
	s_nop 1
	v_cndmask_b32_e32 v236, v236, v77, vcc
	v_cndmask_b32_e64 v237, v237, 24, vcc
	v_cmp_gt_f32_e32 vcc, v78, v236
	s_nop 1
	v_cndmask_b32_e32 v236, v236, v78, vcc
	v_cndmask_b32_e64 v237, v237, 25, vcc
	v_cmp_gt_f32_e32 vcc, v79, v236
	s_nop 1
	v_cndmask_b32_e32 v236, v236, v79, vcc
	v_cndmask_b32_e64 v237, v237, 26, vcc
	v_cmp_gt_f32_e32 vcc, v80, v236
	s_nop 1
	v_cndmask_b32_e32 v236, v236, v80, vcc
	v_cndmask_b32_e64 v237, v237, 27, vcc
	v_cmp_gt_f32_e32 vcc, v81, v236
	s_nop 1
	v_cndmask_b32_e32 v236, v236, v81, vcc
	v_cndmask_b32_e64 v237, v237, 28, vcc
	v_cmp_gt_f32_e32 vcc, v234, v236
	s_nop 1
	v_cndmask_b32_e32 v236, v236, v234, vcc
	v_cndmask_b32_e64 v237, v237, 29, vcc
	v_cmp_le_i32_e32 vcc, 0, v237
	v_lshlrev_b32_e32 v239, v237, v224
	s_nop 0
	v_cndmask_b32_e32 v239, 0, v239, vcc
	v_or_b32_e32 v51, v51, v239
	v_cmp_eq_u32_e64 vcc, 1, v237
	v_cmp_eq_u32_e64 s[0:1], 2, v237
	v_cmp_eq_u32_e64 s[40:41], 3, v237
	v_cndmask_b32_e64 v54, v54, v238, vcc
	v_cmp_eq_u32_e64 vcc, 4, v237
	v_cndmask_b32_e64 v55, v55, v238, s[0:1]
	v_cmp_eq_u32_e64 s[0:1], 5, v237
	v_cndmask_b32_e64 v56, v56, v238, s[40:41]
	v_cmp_eq_u32_e64 s[40:41], 6, v237
	v_cndmask_b32_e64 v57, v57, v238, vcc
	v_cmp_eq_u32_e64 vcc, 7, v237
	v_cndmask_b32_e64 v58, v58, v238, s[0:1]
	v_cmp_eq_u32_e64 s[0:1], 8, v237
	v_cndmask_b32_e64 v59, v59, v238, s[40:41]
	v_cmp_eq_u32_e64 s[40:41], 9, v237
	v_cndmask_b32_e64 v60, v60, v238, vcc
	v_cmp_eq_u32_e64 vcc, 10, v237
	v_cndmask_b32_e64 v61, v61, v238, s[0:1]
	v_cmp_eq_u32_e64 s[0:1], 11, v237
	v_cndmask_b32_e64 v62, v62, v238, s[40:41]
	v_cmp_eq_u32_e64 s[40:41], 12, v237
	v_cndmask_b32_e64 v63, v63, v238, vcc
	v_cmp_eq_u32_e64 vcc, 13, v237
	v_cndmask_b32_e64 v64, v64, v238, s[0:1]
	v_cmp_eq_u32_e64 s[0:1], 14, v237
	v_cndmask_b32_e64 v65, v65, v238, s[40:41]
	v_cmp_eq_u32_e64 s[40:41], 15, v237
	v_cndmask_b32_e64 v66, v66, v238, vcc
	v_cmp_eq_u32_e64 vcc, 16, v237
	v_cndmask_b32_e64 v67, v67, v238, s[0:1]
	v_cmp_eq_u32_e64 s[0:1], 17, v237
	v_cndmask_b32_e64 v68, v68, v238, s[40:41]
	v_cmp_eq_u32_e64 s[40:41], 18, v237
	v_cndmask_b32_e64 v69, v69, v238, vcc
	v_cmp_eq_u32_e64 vcc, 19, v237
	v_cndmask_b32_e64 v70, v70, v238, s[0:1]
	v_cmp_eq_u32_e64 s[0:1], 20, v237
	v_cndmask_b32_e64 v71, v71, v238, s[40:41]
	v_cmp_eq_u32_e64 s[40:41], 21, v237
	v_cndmask_b32_e64 v72, v72, v238, vcc
	v_cmp_eq_u32_e64 vcc, 22, v237
	v_cndmask_b32_e64 v73, v73, v238, s[0:1]
	v_cmp_eq_u32_e64 s[0:1], 23, v237
	v_cndmask_b32_e64 v74, v74, v238, s[40:41]
	v_cmp_eq_u32_e64 s[40:41], 24, v237
	v_cndmask_b32_e64 v75, v75, v238, vcc
	v_cmp_eq_u32_e64 vcc, 25, v237
	v_cndmask_b32_e64 v76, v76, v238, s[0:1]
	v_cmp_eq_u32_e64 s[0:1], 26, v237
	v_cndmask_b32_e64 v77, v77, v238, s[40:41]
	v_cmp_eq_u32_e64 s[40:41], 27, v237
	v_cndmask_b32_e64 v78, v78, v238, vcc
	v_cmp_eq_u32_e64 vcc, 28, v237
	v_cndmask_b32_e64 v79, v79, v238, s[0:1]
	v_cmp_eq_u32_e64 s[0:1], 29, v237
	v_cndmask_b32_e64 v80, v80, v238, s[40:41]
	s_nop 0
	v_cndmask_b32_e64 v81, v81, v238, vcc
	s_nop 0
	v_cndmask_b32_e64 v234, v234, v238, s[0:1]
	v_mov_b32_e32 v236, -1.0
	v_mov_b32_e32 v237, -1
	v_cmp_gt_f32_e32 vcc, v54, v236
	s_nop 1
	v_cndmask_b32_e32 v236, v236, v54, vcc
	v_cndmask_b32_e64 v237, v237, 1, vcc
	v_cmp_gt_f32_e32 vcc, v55, v236
	s_nop 1
	v_cndmask_b32_e32 v236, v236, v55, vcc
	v_cndmask_b32_e64 v237, v237, 2, vcc
	v_cmp_gt_f32_e32 vcc, v56, v236
	s_nop 1
	v_cndmask_b32_e32 v236, v236, v56, vcc
	v_cndmask_b32_e64 v237, v237, 3, vcc
	v_cmp_gt_f32_e32 vcc, v57, v236
	s_nop 1
	v_cndmask_b32_e32 v236, v236, v57, vcc
	v_cndmask_b32_e64 v237, v237, 4, vcc
	v_cmp_gt_f32_e32 vcc, v58, v236
	s_nop 1
	v_cndmask_b32_e32 v236, v236, v58, vcc
	v_cndmask_b32_e64 v237, v237, 5, vcc
	v_cmp_gt_f32_e32 vcc, v59, v236
	s_nop 1
	v_cndmask_b32_e32 v236, v236, v59, vcc
	v_cndmask_b32_e64 v237, v237, 6, vcc
	v_cmp_gt_f32_e32 vcc, v60, v236
	s_nop 1
	v_cndmask_b32_e32 v236, v236, v60, vcc
	v_cndmask_b32_e64 v237, v237, 7, vcc
	v_cmp_gt_f32_e32 vcc, v61, v236
	s_nop 1
	v_cndmask_b32_e32 v236, v236, v61, vcc
	v_cndmask_b32_e64 v237, v237, 8, vcc
	v_cmp_gt_f32_e32 vcc, v62, v236
	s_nop 1
	v_cndmask_b32_e32 v236, v236, v62, vcc
	v_cndmask_b32_e64 v237, v237, 9, vcc
	v_cmp_gt_f32_e32 vcc, v63, v236
	s_nop 1
	v_cndmask_b32_e32 v236, v236, v63, vcc
	v_cndmask_b32_e64 v237, v237, 10, vcc
	v_cmp_gt_f32_e32 vcc, v64, v236
	s_nop 1
	v_cndmask_b32_e32 v236, v236, v64, vcc
	v_cndmask_b32_e64 v237, v237, 11, vcc
	v_cmp_gt_f32_e32 vcc, v65, v236
	s_nop 1
	v_cndmask_b32_e32 v236, v236, v65, vcc
	v_cndmask_b32_e64 v237, v237, 12, vcc
	v_cmp_gt_f32_e32 vcc, v66, v236
	s_nop 1
	v_cndmask_b32_e32 v236, v236, v66, vcc
	v_cndmask_b32_e64 v237, v237, 13, vcc
	v_cmp_gt_f32_e32 vcc, v67, v236
	s_nop 1
	v_cndmask_b32_e32 v236, v236, v67, vcc
	v_cndmask_b32_e64 v237, v237, 14, vcc
	v_cmp_gt_f32_e32 vcc, v68, v236
	s_nop 1
	v_cndmask_b32_e32 v236, v236, v68, vcc
	v_cndmask_b32_e64 v237, v237, 15, vcc
; DEVI void nsa_item(const Params& p, int l, int item, char* lds_raw, volatile int* nsa_cnt) {
;     ...
;     while (cnt < 8) {
;       int best = -1;
;       float bv = -1.f;
;       for (int J = 0; J <= cur; ++J) {
;         float v = Pb[tid * 33 + J];
;         if (!((sel >> J) & 1u) && v > bv) { bv = v; best = J; }
;       }
;       if (best < 0) break;
;       sel |= 1u << best;
;       ++cnt;
;     }
	v_cmp_gt_f32_e32 vcc, v69, v236
	s_nop 1
	v_cndmask_b32_e32 v236, v236, v69, vcc
	v_cndmask_b32_e64 v237, v237, 16, vcc
	v_cmp_gt_f32_e32 vcc, v70, v236
	s_nop 1
	v_cndmask_b32_e32 v236, v236, v70, vcc
	v_cndmask_b32_e64 v237, v237, 17, vcc
	v_cmp_gt_f32_e32 vcc, v71, v236
	s_nop 1
	v_cndmask_b32_e32 v236, v236, v71, vcc
	v_cndmask_b32_e64 v237, v237, 18, vcc
	v_cmp_gt_f32_e32 vcc, v72, v236
	s_nop 1
	v_cndmask_b32_e32 v236, v236, v72, vcc
	v_cndmask_b32_e64 v237, v237, 19, vcc
	v_cmp_gt_f32_e32 vcc, v73, v236
	s_nop 1
	v_cndmask_b32_e32 v236, v236, v73, vcc
	v_cndmask_b32_e64 v237, v237, 20, vcc
	v_cmp_gt_f32_e32 vcc, v74, v236
	s_nop 1
	v_cndmask_b32_e32 v236, v236, v74, vcc
	v_cndmask_b32_e64 v237, v237, 21, vcc
	v_cmp_gt_f32_e32 vcc, v75, v236
	s_nop 1
	v_cndmask_b32_e32 v236, v236, v75, vcc
	v_cndmask_b32_e64 v237, v237, 22, vcc
	v_cmp_gt_f32_e32 vcc, v76, v236
	s_nop 1
	v_cndmask_b32_e32 v236, v236, v76, vcc
	v_cndmask_b32_e64 v237, v237, 23, vcc
	v_cmp_gt_f32_e32 vcc, v77, v236
	s_nop 1
	v_cndmask_b32_e32 v236, v236, v77, vcc
	v_cndmask_b32_e64 v237, v237, 24, vcc
	v_cmp_gt_f32_e32 vcc, v78, v236
	s_nop 1
	v_cndmask_b32_e32 v236, v236, v78, vcc
	v_cndmask_b32_e64 v237, v237, 25, vcc
	v_cmp_gt_f32_e32 vcc, v79, v236
	s_nop 1
	v_cndmask_b32_e32 v236, v236, v79, vcc
	v_cndmask_b32_e64 v237, v237, 26, vcc
	v_cmp_gt_f32_e32 vcc, v80, v236
	s_nop 1
	v_cndmask_b32_e32 v236, v236, v80, vcc
	v_cndmask_b32_e64 v237, v237, 27, vcc
	v_cmp_gt_f32_e32 vcc, v81, v236
	s_nop 1
	v_cndmask_b32_e32 v236, v236, v81, vcc
	v_cndmask_b32_e64 v237, v237, 28, vcc
	v_cmp_gt_f32_e32 vcc, v234, v236
	s_nop 1
	v_cndmask_b32_e32 v236, v236, v234, vcc
	v_cndmask_b32_e64 v237, v237, 29, vcc
	v_cmp_le_i32_e32 vcc, 0, v237
	v_lshlrev_b32_e32 v239, v237, v224
	s_nop 0
	v_cndmask_b32_e32 v239, 0, v239, vcc
	v_or_b32_e32 v51, v51, v239
	v_cmp_eq_u32_e64 vcc, 1, v237
	v_cmp_eq_u32_e64 s[0:1], 2, v237
	v_cmp_eq_u32_e64 s[40:41], 3, v237
	v_cndmask_b32_e64 v54, v54, v238, vcc
	v_cmp_eq_u32_e64 vcc, 4, v237
	v_cndmask_b32_e64 v55, v55, v238, s[0:1]
	v_cmp_eq_u32_e64 s[0:1], 5, v237
	v_cndmask_b32_e64 v56, v56, v238, s[40:41]
	v_cmp_eq_u32_e64 s[40:41], 6, v237
	v_cndmask_b32_e64 v57, v57, v238, vcc
	v_cmp_eq_u32_e64 vcc, 7, v237
	v_cndmask_b32_e64 v58, v58, v238, s[0:1]
	v_cmp_eq_u32_e64 s[0:1], 8, v237
	v_cndmask_b32_e64 v59, v59, v238, s[40:41]
	v_cmp_eq_u32_e64 s[40:41], 9, v237
	v_cndmask_b32_e64 v60, v60, v238, vcc
	v_cmp_eq_u32_e64 vcc, 10, v237
	v_cndmask_b32_e64 v61, v61, v238, s[0:1]
	v_cmp_eq_u32_e64 s[0:1], 11, v237
	v_cndmask_b32_e64 v62, v62, v238, s[40:41]
	v_cmp_eq_u32_e64 s[40:41], 12, v237
	v_cndmask_b32_e64 v63, v63, v238, vcc
	v_cmp_eq_u32_e64 vcc, 13, v237
	v_cndmask_b32_e64 v64, v64, v238, s[0:1]
	v_cmp_eq_u32_e64 s[0:1], 14, v237
	v_cndmask_b32_e64 v65, v65, v238, s[40:41]
	v_cmp_eq_u32_e64 s[40:41], 15, v237
	v_cndmask_b32_e64 v66, v66, v238, vcc
	v_cmp_eq_u32_e64 vcc, 16, v237
	v_cndmask_b32_e64 v67, v67, v238, s[0:1]
	v_cmp_eq_u32_e64 s[0:1], 17, v237
	v_cndmask_b32_e64 v68, v68, v238, s[40:41]
	v_cmp_eq_u32_e64 s[40:41], 18, v237
	v_cndmask_b32_e64 v69, v69, v238, vcc
	v_cmp_eq_u32_e64 vcc, 19, v237
	v_cndmask_b32_e64 v70, v70, v238, s[0:1]
	v_cmp_eq_u32_e64 s[0:1], 20, v237
	v_cndmask_b32_e64 v71, v71, v238, s[40:41]
	v_cmp_eq_u32_e64 s[40:41], 21, v237
	v_cndmask_b32_e64 v72, v72, v238, vcc
	v_cmp_eq_u32_e64 vcc, 22, v237
	v_cndmask_b32_e64 v73, v73, v238, s[0:1]
	v_cmp_eq_u32_e64 s[0:1], 23, v237
	v_cndmask_b32_e64 v74, v74, v238, s[40:41]
	v_cmp_eq_u32_e64 s[40:41], 24, v237
	v_cndmask_b32_e64 v75, v75, v238, vcc
	v_cmp_eq_u32_e64 vcc, 25, v237
	v_cndmask_b32_e64 v76, v76, v238, s[0:1]
	v_cmp_eq_u32_e64 s[0:1], 26, v237
	v_cndmask_b32_e64 v77, v77, v238, s[40:41]
	v_cmp_eq_u32_e64 s[40:41], 27, v237
	v_cndmask_b32_e64 v78, v78, v238, vcc
	v_cmp_eq_u32_e64 vcc, 28, v237
	v_cndmask_b32_e64 v79, v79, v238, s[0:1]
	v_cmp_eq_u32_e64 s[0:1], 29, v237
	v_cndmask_b32_e64 v80, v80, v238, s[40:41]
	s_nop 0
	v_cndmask_b32_e64 v81, v81, v238, vcc
	s_nop 0
	v_cndmask_b32_e64 v234, v234, v238, s[0:1]
	v_mov_b32_e32 v236, -1.0
	v_mov_b32_e32 v237, -1
	v_cmp_gt_f32_e32 vcc, v54, v236
	s_nop 1
	v_cndmask_b32_e32 v236, v236, v54, vcc
	v_cndmask_b32_e64 v237, v237, 1, vcc
	v_cmp_gt_f32_e32 vcc, v55, v236
	s_nop 1
	v_cndmask_b32_e32 v236, v236, v55, vcc
	v_cndmask_b32_e64 v237, v237, 2, vcc
	v_cmp_gt_f32_e32 vcc, v56, v236
	s_nop 1
	v_cndmask_b32_e32 v236, v236, v56, vcc
	v_cndmask_b32_e64 v237, v237, 3, vcc
	v_cmp_gt_f32_e32 vcc, v57, v236
	s_nop 1
	v_cndmask_b32_e32 v236, v236, v57, vcc
	v_cndmask_b32_e64 v237, v237, 4, vcc
	v_cmp_gt_f32_e32 vcc, v58, v236
	s_nop 1
	v_cndmask_b32_e32 v236, v236, v58, vcc
	v_cndmask_b32_e64 v237, v237, 5, vcc
	v_cmp_gt_f32_e32 vcc, v59, v236
	s_nop 1
	v_cndmask_b32_e32 v236, v236, v59, vcc
	v_cndmask_b32_e64 v237, v237, 6, vcc
	v_cmp_gt_f32_e32 vcc, v60, v236
	s_nop 1
	v_cndmask_b32_e32 v236, v236, v60, vcc
	v_cndmask_b32_e64 v237, v237, 7, vcc
	v_cmp_gt_f32_e32 vcc, v61, v236
	s_nop 1
	v_cndmask_b32_e32 v236, v236, v61, vcc
	v_cndmask_b32_e64 v237, v237, 8, vcc
	v_cmp_gt_f32_e32 vcc, v62, v236
	s_nop 1
	v_cndmask_b32_e32 v236, v236, v62, vcc
	v_cndmask_b32_e64 v237, v237, 9, vcc
	v_cmp_gt_f32_e32 vcc, v63, v236
	s_nop 1
	v_cndmask_b32_e32 v236, v236, v63, vcc
	v_cndmask_b32_e64 v237, v237, 10, vcc
	v_cmp_gt_f32_e32 vcc, v64, v236
	s_nop 1
	v_cndmask_b32_e32 v236, v236, v64, vcc
	v_cndmask_b32_e64 v237, v237, 11, vcc
	v_cmp_gt_f32_e32 vcc, v65, v236
	s_nop 1
	v_cndmask_b32_e32 v236, v236, v65, vcc
	v_cndmask_b32_e64 v237, v237, 12, vcc
	v_cmp_gt_f32_e32 vcc, v66, v236
	s_nop 1
	v_cndmask_b32_e32 v236, v236, v66, vcc
; DEVI void nsa_item(const Params& p, int l, int item, char* lds_raw, volatile int* nsa_cnt) {
;     ...
;     while (cnt < 8) {
;       int best = -1;
;       float bv = -1.f;
;       for (int J = 0; J <= cur; ++J) {
;         float v = Pb[tid * 33 + J];
;         if (!((sel >> J) & 1u) && v > bv) { bv = v; best = J; }
;       }
;       if (best < 0) break;
;       sel |= 1u << best;
;       ++cnt;
;     }
	v_cndmask_b32_e64 v237, v237, 13, vcc
	v_cmp_gt_f32_e32 vcc, v67, v236
	s_nop 1
	v_cndmask_b32_e32 v236, v236, v67, vcc
	v_cndmask_b32_e64 v237, v237, 14, vcc
	v_cmp_gt_f32_e32 vcc, v68, v236
	s_nop 1
	v_cndmask_b32_e32 v236, v236, v68, vcc
	v_cndmask_b32_e64 v237, v237, 15, vcc
	v_cmp_gt_f32_e32 vcc, v69, v236
	s_nop 1
	v_cndmask_b32_e32 v236, v236, v69, vcc
	v_cndmask_b32_e64 v237, v237, 16, vcc
	v_cmp_gt_f32_e32 vcc, v70, v236
	s_nop 1
	v_cndmask_b32_e32 v236, v236, v70, vcc
	v_cndmask_b32_e64 v237, v237, 17, vcc
	v_cmp_gt_f32_e32 vcc, v71, v236
	s_nop 1
	v_cndmask_b32_e32 v236, v236, v71, vcc
	v_cndmask_b32_e64 v237, v237, 18, vcc
	v_cmp_gt_f32_e32 vcc, v72, v236
	s_nop 1
	v_cndmask_b32_e32 v236, v236, v72, vcc
	v_cndmask_b32_e64 v237, v237, 19, vcc
	v_cmp_gt_f32_e32 vcc, v73, v236
	s_nop 1
	v_cndmask_b32_e32 v236, v236, v73, vcc
	v_cndmask_b32_e64 v237, v237, 20, vcc
	v_cmp_gt_f32_e32 vcc, v74, v236
	s_nop 1
	v_cndmask_b32_e32 v236, v236, v74, vcc
	v_cndmask_b32_e64 v237, v237, 21, vcc
	v_cmp_gt_f32_e32 vcc, v75, v236
	s_nop 1
	v_cndmask_b32_e32 v236, v236, v75, vcc
	v_cndmask_b32_e64 v237, v237, 22, vcc
	v_cmp_gt_f32_e32 vcc, v76, v236
	s_nop 1
	v_cndmask_b32_e32 v236, v236, v76, vcc
	v_cndmask_b32_e64 v237, v237, 23, vcc
	v_cmp_gt_f32_e32 vcc, v77, v236
	s_nop 1
	v_cndmask_b32_e32 v236, v236, v77, vcc
	v_cndmask_b32_e64 v237, v237, 24, vcc
	v_cmp_gt_f32_e32 vcc, v78, v236
	s_nop 1
	v_cndmask_b32_e32 v236, v236, v78, vcc
	v_cndmask_b32_e64 v237, v237, 25, vcc
	v_cmp_gt_f32_e32 vcc, v79, v236
	s_nop 1
	v_cndmask_b32_e32 v236, v236, v79, vcc
	v_cndmask_b32_e64 v237, v237, 26, vcc
	v_cmp_gt_f32_e32 vcc, v80, v236
	s_nop 1
	v_cndmask_b32_e32 v236, v236, v80, vcc
	v_cndmask_b32_e64 v237, v237, 27, vcc
	v_cmp_gt_f32_e32 vcc, v81, v236
	s_nop 1
	v_cndmask_b32_e32 v236, v236, v81, vcc
	v_cndmask_b32_e64 v237, v237, 28, vcc
	v_cmp_gt_f32_e32 vcc, v234, v236
	s_nop 1
	v_cndmask_b32_e32 v236, v236, v234, vcc
	v_cndmask_b32_e64 v237, v237, 29, vcc
	v_cmp_le_i32_e32 vcc, 0, v237
	v_lshlrev_b32_e32 v239, v237, v224
	s_nop 0
	v_cndmask_b32_e32 v239, 0, v239, vcc
	v_or_b32_e32 v51, v51, v239
	v_cmp_eq_u32_e64 vcc, 1, v237
	v_cmp_eq_u32_e64 s[0:1], 2, v237
	v_cmp_eq_u32_e64 s[40:41], 3, v237
	v_cndmask_b32_e64 v54, v54, v238, vcc
	v_cmp_eq_u32_e64 vcc, 4, v237
	v_cndmask_b32_e64 v55, v55, v238, s[0:1]
	v_cmp_eq_u32_e64 s[0:1], 5, v237
	v_cndmask_b32_e64 v56, v56, v238, s[40:41]
	v_cmp_eq_u32_e64 s[40:41], 6, v237
	v_cndmask_b32_e64 v57, v57, v238, vcc
	v_cmp_eq_u32_e64 vcc, 7, v237
	v_cndmask_b32_e64 v58, v58, v238, s[0:1]
	v_cmp_eq_u32_e64 s[0:1], 8, v237
	v_cndmask_b32_e64 v59, v59, v238, s[40:41]
	v_cmp_eq_u32_e64 s[40:41], 9, v237
	v_cndmask_b32_e64 v60, v60, v238, vcc
	v_cmp_eq_u32_e64 vcc, 10, v237
	v_cndmask_b32_e64 v61, v61, v238, s[0:1]
	v_cmp_eq_u32_e64 s[0:1], 11, v237
	v_cndmask_b32_e64 v62, v62, v238, s[40:41]
	v_cmp_eq_u32_e64 s[40:41], 12, v237
	v_cndmask_b32_e64 v63, v63, v238, vcc
	v_cmp_eq_u32_e64 vcc, 13, v237
	v_cndmask_b32_e64 v64, v64, v238, s[0:1]
	v_cmp_eq_u32_e64 s[0:1], 14, v237
	v_cndmask_b32_e64 v65, v65, v238, s[40:41]
	v_cmp_eq_u32_e64 s[40:41], 15, v237
	v_cndmask_b32_e64 v66, v66, v238, vcc
	v_cmp_eq_u32_e64 vcc, 16, v237
	v_cndmask_b32_e64 v67, v67, v238, s[0:1]
	v_cmp_eq_u32_e64 s[0:1], 17, v237
	v_cndmask_b32_e64 v68, v68, v238, s[40:41]
	v_cmp_eq_u32_e64 s[40:41], 18, v237
	v_cndmask_b32_e64 v69, v69, v238, vcc
	v_cmp_eq_u32_e64 vcc, 19, v237
	v_cndmask_b32_e64 v70, v70, v238, s[0:1]
	v_cmp_eq_u32_e64 s[0:1], 20, v237
	v_cndmask_b32_e64 v71, v71, v238, s[40:41]
	v_cmp_eq_u32_e64 s[40:41], 21, v237
	v_cndmask_b32_e64 v72, v72, v238, vcc
	v_cmp_eq_u32_e64 vcc, 22, v237
	v_cndmask_b32_e64 v73, v73, v238, s[0:1]
	v_cmp_eq_u32_e64 s[0:1], 23, v237
	v_cndmask_b32_e64 v74, v74, v238, s[40:41]
	v_cmp_eq_u32_e64 s[40:41], 24, v237
	v_cndmask_b32_e64 v75, v75, v238, vcc
	v_cmp_eq_u32_e64 vcc, 25, v237
	v_cndmask_b32_e64 v76, v76, v238, s[0:1]
	v_cmp_eq_u32_e64 s[0:1], 26, v237
	v_cndmask_b32_e64 v77, v77, v238, s[40:41]
	v_cmp_eq_u32_e64 s[40:41], 27, v237
	v_cndmask_b32_e64 v78, v78, v238, vcc
	v_cmp_eq_u32_e64 vcc, 28, v237
	v_cndmask_b32_e64 v79, v79, v238, s[0:1]
	v_cmp_eq_u32_e64 s[0:1], 29, v237
	v_cndmask_b32_e64 v80, v80, v238, s[40:41]
	s_nop 0
	v_cndmask_b32_e64 v81, v81, v238, vcc
	s_nop 0
	v_cndmask_b32_e64 v234, v234, v238, s[0:1]
	v_mov_b32_e32 v236, -1.0
	v_mov_b32_e32 v237, -1
	v_cmp_gt_f32_e32 vcc, v54, v236
	s_nop 1
	v_cndmask_b32_e32 v236, v236, v54, vcc
	v_cndmask_b32_e64 v237, v237, 1, vcc
	v_cmp_gt_f32_e32 vcc, v55, v236
	s_nop 1
	v_cndmask_b32_e32 v236, v236, v55, vcc
	v_cndmask_b32_e64 v237, v237, 2, vcc
	v_cmp_gt_f32_e32 vcc, v56, v236
	s_nop 1
; DEVI void nsa_item(const Params& p, int l, int item, char* lds_raw, volatile int* nsa_cnt) {
;     ...
;     while (cnt < 8) {
;       int best = -1;
;       float bv = -1.f;
;       for (int J = 0; J <= cur; ++J) {
;         float v = Pb[tid * 33 + J];
;         if (!((sel >> J) & 1u) && v > bv) { bv = v; best = J; }
;       }
;       if (best < 0) break;
;       sel |= 1u << best;
;       ++cnt;
;     }
;     selm[tid] = sel;
;     unsigned om = sel;
; #pragma unroll
;     for (int o = 32; o >= 1; o >>= 1) om |= (unsigned)__shfl_xor((int)om, o);
;     if (tid == 0) selm[64] = om;
	v_cndmask_b32_e32 v236, v236, v56, vcc
	v_cndmask_b32_e64 v237, v237, 3, vcc
	v_cmp_gt_f32_e32 vcc, v57, v236
	s_nop 1
	v_cndmask_b32_e32 v236, v236, v57, vcc
	v_cndmask_b32_e64 v237, v237, 4, vcc
	v_cmp_gt_f32_e32 vcc, v58, v236
	s_nop 1
	v_cndmask_b32_e32 v236, v236, v58, vcc
	v_cndmask_b32_e64 v237, v237, 5, vcc
	v_cmp_gt_f32_e32 vcc, v59, v236
	s_nop 1
	v_cndmask_b32_e32 v236, v236, v59, vcc
	v_cndmask_b32_e64 v237, v237, 6, vcc
	v_cmp_gt_f32_e32 vcc, v60, v236
	s_nop 1
	v_cndmask_b32_e32 v236, v236, v60, vcc
	v_cndmask_b32_e64 v237, v237, 7, vcc
	v_cmp_gt_f32_e32 vcc, v61, v236
	s_nop 1
	v_cndmask_b32_e32 v236, v236, v61, vcc
	v_cndmask_b32_e64 v237, v237, 8, vcc
	v_cmp_gt_f32_e32 vcc, v62, v236
	s_nop 1
	v_cndmask_b32_e32 v236, v236, v62, vcc
	v_cndmask_b32_e64 v237, v237, 9, vcc
	v_cmp_gt_f32_e32 vcc, v63, v236
	s_nop 1
	v_cndmask_b32_e32 v236, v236, v63, vcc
	v_cndmask_b32_e64 v237, v237, 10, vcc
	v_cmp_gt_f32_e32 vcc, v64, v236
	s_nop 1
	v_cndmask_b32_e32 v236, v236, v64, vcc
	v_cndmask_b32_e64 v237, v237, 11, vcc
	v_cmp_gt_f32_e32 vcc, v65, v236
	s_nop 1
	v_cndmask_b32_e32 v236, v236, v65, vcc
	v_cndmask_b32_e64 v237, v237, 12, vcc
	v_cmp_gt_f32_e32 vcc, v66, v236
	s_nop 1
	v_cndmask_b32_e32 v236, v236, v66, vcc
	v_cndmask_b32_e64 v237, v237, 13, vcc
	v_cmp_gt_f32_e32 vcc, v67, v236
	s_nop 1
	v_cndmask_b32_e32 v236, v236, v67, vcc
	v_cndmask_b32_e64 v237, v237, 14, vcc
	v_cmp_gt_f32_e32 vcc, v68, v236
	s_nop 1
	v_cndmask_b32_e32 v236, v236, v68, vcc
	v_cndmask_b32_e64 v237, v237, 15, vcc
	v_cmp_gt_f32_e32 vcc, v69, v236
	s_nop 1
	v_cndmask_b32_e32 v236, v236, v69, vcc
	v_cndmask_b32_e64 v237, v237, 16, vcc
	v_cmp_gt_f32_e32 vcc, v70, v236
	s_nop 1
	v_cndmask_b32_e32 v236, v236, v70, vcc
	v_cndmask_b32_e64 v237, v237, 17, vcc
	v_cmp_gt_f32_e32 vcc, v71, v236
	s_nop 1
	v_cndmask_b32_e32 v236, v236, v71, vcc
	v_cndmask_b32_e64 v237, v237, 18, vcc
	v_cmp_gt_f32_e32 vcc, v72, v236
	s_nop 1
	v_cndmask_b32_e32 v236, v236, v72, vcc
	v_cndmask_b32_e64 v237, v237, 19, vcc
	v_cmp_gt_f32_e32 vcc, v73, v236
	s_nop 1
	v_cndmask_b32_e32 v236, v236, v73, vcc
	v_cndmask_b32_e64 v237, v237, 20, vcc
	v_cmp_gt_f32_e32 vcc, v74, v236
	s_nop 1
	v_cndmask_b32_e32 v236, v236, v74, vcc
	v_cndmask_b32_e64 v237, v237, 21, vcc
	v_cmp_gt_f32_e32 vcc, v75, v236
	s_nop 1
	v_cndmask_b32_e32 v236, v236, v75, vcc
	v_cndmask_b32_e64 v237, v237, 22, vcc
	v_cmp_gt_f32_e32 vcc, v76, v236
	s_nop 1
	v_cndmask_b32_e32 v236, v236, v76, vcc
	v_cndmask_b32_e64 v237, v237, 23, vcc
	v_cmp_gt_f32_e32 vcc, v77, v236
	s_nop 1
	v_cndmask_b32_e32 v236, v236, v77, vcc
	v_cndmask_b32_e64 v237, v237, 24, vcc
	v_cmp_gt_f32_e32 vcc, v78, v236
	s_nop 1
	v_cndmask_b32_e32 v236, v236, v78, vcc
	v_cndmask_b32_e64 v237, v237, 25, vcc
	v_cmp_gt_f32_e32 vcc, v79, v236
	s_nop 1
	v_cndmask_b32_e32 v236, v236, v79, vcc
	v_cndmask_b32_e64 v237, v237, 26, vcc
	v_cmp_gt_f32_e32 vcc, v80, v236
	s_nop 1
	v_cndmask_b32_e32 v236, v236, v80, vcc
	v_cndmask_b32_e64 v237, v237, 27, vcc
	v_cmp_gt_f32_e32 vcc, v81, v236
	s_nop 1
	v_cndmask_b32_e32 v236, v236, v81, vcc
	v_cndmask_b32_e64 v237, v237, 28, vcc
	v_cmp_gt_f32_e32 vcc, v234, v236
	s_nop 1
	v_cndmask_b32_e32 v236, v236, v234, vcc
	v_cndmask_b32_e64 v237, v237, 29, vcc
	v_cmp_le_i32_e32 vcc, 0, v237
	v_lshlrev_b32_e32 v239, v237, v224
	s_nop 0
	v_cndmask_b32_e32 v239, 0, v239, vcc
	v_or_b32_e32 v51, v51, v239
	v_mov_b32_e32 v53, v51
	v_lshlrev_b32_e32 v50, 7, v83
	v_sub_u32_e32 v50, v52, v50
	ds_write_b32 v50, v53 offset:62208
	ds_bpermute_b32 v50, v202, v53
	s_waitcnt lgkmcnt(0)
	v_or_b32_e32 v50, v50, v53
	ds_bpermute_b32 v51, v201, v50
	s_waitcnt lgkmcnt(0)
	v_or_b32_e32 v50, v51, v50
	v_xor_b32_e32 v51, 8, v225
	v_cmp_lt_i32_e32 vcc, v51, v92
	s_nop 1
	v_cndmask_b32_e32 v51, v225, v51, vcc
	v_lshlrev_b32_e32 v51, 2, v51
	ds_bpermute_b32 v51, v51, v50
	s_waitcnt lgkmcnt(0)
	v_or_b32_e32 v50, v51, v50
	v_xor_b32_e32 v51, 4, v225
	v_cmp_lt_i32_e32 vcc, v51, v92
	s_nop 1
	v_cndmask_b32_e32 v51, v225, v51, vcc
	v_lshlrev_b32_e32 v51, 2, v51
	ds_bpermute_b32 v51, v51, v50
	s_waitcnt lgkmcnt(0)
	v_or_b32_e32 v50, v51, v50
	v_xor_b32_e32 v51, 2, v225
	v_cmp_lt_i32_e32 vcc, v51, v92
	s_nop 1
	v_cndmask_b32_e32 v51, v225, v51, vcc
	v_lshlrev_b32_e32 v51, 2, v51
	ds_bpermute_b32 v51, v51, v50
	s_waitcnt lgkmcnt(0)
	v_or_b32_e32 v50, v51, v50
	v_xor_b32_e32 v51, 1, v225
	v_cmp_lt_i32_e32 vcc, v51, v92
	s_nop 1
	v_cndmask_b32_e32 v51, v225, v51, vcc
	v_lshlrev_b32_e32 v51, 2, v51
	ds_bpermute_b32 v51, v51, v50
	v_cmp_eq_u32_e32 vcc, 0, v83
	s_and_b64 exec, exec, vcc
	s_cbranch_execz .LBB0_498
	s_waitcnt lgkmcnt(0)
	v_or_b32_e32 v50, v51, v50
	v_mov_b32_e32 v51, s26
	ds_write_b32 v51, v50 offset:62464
